# layer-0 phase-3 gemv passes: 2nd/3rd pass job map rotated so no wave owns more than one job
# speedup vs baseline: 1.1359x; 1.0050x over previous
.LBB0_745:
	v_mov_b32_e32 v0, v216
	v_readlane_b32 s1, v249, 25
	v_readfirstlane_b32 s0, v0
	s_ashr_i32 s0, s0, 6
	s_add_i32 s10, s0, s1
	s_addk_i32 s10, 0x780
	s_and_b32 s10, s10, 0x7ff
	s_cmpk_gt_i32 s10, 0xff
	s_cbranch_scc1 .LBB0_752
	v_and_b32_e32 v10, 63, v0
	s_branch .LBB0_748

.LBB0_752:
	v_mov_b32_e32 v0, v216
	v_readlane_b32 s1, v249, 25
	v_readfirstlane_b32 s0, v0
	s_ashr_i32 s0, s0, 6
	s_add_i32 s10, s0, s1
	s_addk_i32 s10, 0x680
	s_and_b32 s10, s10, 0x7ff
	s_cmpk_gt_i32 s10, 0x7f
	s_cbranch_scc1 .LBB0_759
	v_and_b32_e32 v10, 63, v0
	s_branch .LBB0_755
